# x15 + layer-1 weight conversion moved from the prologue into the tail of the layer-0 attention phase (items claimed from a work counter, before the grid barrier)
# baseline (speedup 1.0000x reference)
.Lst_claim:
	s_waitcnt vmcnt(4)
	v_readfirstlane_b32 s30, v140
	s_add_i32 s30, s30, 0x8200
	s_add_i32 s30, s30, s0
	s_lshl_b32 s28, s30, 5
	s_branch .Lst_next
.Lpp_done:
	s_waitcnt vmcnt(0) lgkmcnt(0)
	s_barrier
	s_mov_b32 s101, 0x81ff
	s_branch .LBB0_636

.LBB0_4:
	v_writelane_b32 v254, s2, 44
	v_mov_b32_e32 v194, v238
	v_readlane_b32 s0, v254, 0
	v_readlane_b32 s1, v254, 1
	s_load_dwordx2 s[94:95], s[0:1], 0x60
	s_load_dwordx16 s[56:71], s[0:1], 0x0
	s_load_dwordx8 s[8:15], s[0:1], 0x40
	v_readfirstlane_b32 s2, v194
	s_ashr_i32 s86, s2, 6
	v_and_b32_e32 v240, 63, v194
	s_mov_b32 s91, s5
	s_waitcnt lgkmcnt(0)
	v_writelane_b32 v254, s8, 45
	s_nop 1
	v_writelane_b32 v254, s9, 46
	v_writelane_b32 v254, s10, 47
	v_writelane_b32 v254, s11, 48
	v_writelane_b32 v254, s12, 49
	v_writelane_b32 v254, s13, 50
	v_writelane_b32 v254, s14, 51
	v_writelane_b32 v254, s15, 52
	s_nop 0
	v_readlane_b32 s0, v254, 4
	v_readlane_b32 s1, v254, 5
	s_load_dword s0, s[0:1], 0x0
	s_waitcnt lgkmcnt(0)
	v_writelane_b32 v254, s0, 53
	s_add_u32 s0, s94, 0x10000
	s_addc_u32 s1, s95, 0
	v_writelane_b32 v254, s0, 54
	s_nop 0
	s_nop 0
	v_writelane_b32 v254, s1, 55
	s_cmp_lg_u32 s100, 2
	s_cbranch_scc1 .Lpp_no
	s_mov_b32 s100, 1
	s_mov_b32 s101, 0x103ff
	s_mov_b64 s[0:1], -1
	s_branch .LBB0_465

.LBB0_470:
	s_cmp_eq_u32 s101, 0x103ff
	s_cbranch_scc1 .Lst_claim
	s_add_i32 s30, s30, s0
	s_add_i32 s28, s28, s29
.Lst_next:
	s_cmp_gt_i32 s30, s101
	s_cbranch_scc1 .LBB0_615
.LBB0_471:
	s_cmp_lg_u32 s101, 0x103ff
	s_cbranch_scc1 .Lst_noclaim
	s_mov_b64 s[84:85], exec
	v_readlane_b32 s6, v254, 42
	v_readlane_b32 s7, v254, 43
	s_mov_b64 exec, 1
	s_nop 1
	v_mov_b32_e32 v140, 1
	s_nop 3
	global_atomic_add v140, v65, v140, s[6:7] offset:3840 sc0
	s_mov_b64 exec, s[84:85]

.LBB0_636:
	s_cmp_lg_u32 s91, 3
	s_cbranch_scc1 .Lst_skip
	s_cmp_lg_u32 s100, 0
	s_cbranch_scc1 .Lst_skip
	s_mov_b32 s100, 2
	s_mov_b32 s5, 3
	v_readlane_b32 s2, v254, 44
	s_branch .LBB0_4
